# CD rec sample RG-LRU item: the nine loads of the 4-step recurrence issued together with one wait (was four serial round trips)
# baseline (speedup 1.0000x reference)
; __device__ __forceinline__ unsigned f2bf(float f) { return cvtpk(f, 0.f) & 0xffffu; }
; __device__ __forceinline__ void seq_info(int s, int& row0, int& L) { if (s < 4) { row0 = s << 11; L = 2048; } else { row0 = TP + ((s - 4) << 2); L = 4; } }
; __device__ __forceinline__ void phase_cd_rec(const KP kp, const int bid, const int G, int j, int li, LAS unsigned char* lds, int tid0) {
;     ...
;     for (;;) {
;         __syncthreads();
;         if (tid0 == 0) qslot[0] = __hip_atomic_fetch_add(qhead, 1u, __ATOMIC_RELAXED, __HIP_MEMORY_SCOPE_AGENT);
;         __syncthreads();
;         const int it = (int)qslot[0];
;         if (it >= 1024) break;
;     ...
;             const int q_ = it - 768, s = 4 + (q_ >> 1), h = q_ & 1; int row0, L; seq_info(s, row0, L);
;             const int ch = h * 512 + tid;
;             float hh = s < 4 ? 0.f : kp.in(7)[((size_t)j * 128 + (s - 4)) * 1024 + ch];
; #pragma unroll 8
;             for (int t = 0; t < L; ++t) { const size_t r = (size_t)(row0 + t); hh = LA[r * 1024 + ch] * hh + LB[r * 1024 + ch]; HS[r * 1024 + ch] = (bf16)f2bf(hh); }
;             float* dst = s < 4 ? kp.out() + O_LRU_P + ((size_t)j * 4 + s) * 1024 : kp.out() + O_LRU_S + ((size_t)j * 128 + (s - 4)) * 1024;
;             dst[ch] = hh;
.LBB0_158:
	s_or_b64 exec, exec, s[0:1]
	v_mov_b32_e32 v0, s34
	s_waitcnt lgkmcnt(0)
	s_barrier
	ds_read_b32 v0, v0
	s_mov_b64 s[0:1], -1
	s_waitcnt lgkmcnt(0)
	v_cmp_lt_i32_e32 vcc, s27, v0
	v_readfirstlane_b32 s9, v0
	s_cbranch_vccnz .LBB0_153
	v_mov_b32_e32 v34, v183
	s_cmpk_gt_i32 s9, 0xff
	s_cbranch_scc0 .LBB0_177
	s_cmpk_gt_u32 s9, 0x2ff
	s_cbranch_scc0 .LBB0_162
	s_add_i32 s0, s9, 0xfffffd00
	s_lshr_b32 s0, s0, 1
	s_lshl_b32 s4, s0, 2
	s_lshl_b32 s1, s9, 9
	s_load_dwordx2 s[2:3], s[60:61], 0x38
	s_add_i32 s38, s4, 0x2000
	s_and_b32 s1, s1, 0x200
	s_add_u32 s0, s82, s0
	v_add_u32_e32 v4, s1, v34
	s_addc_u32 s1, s83, 0
	s_lshl_b64 s[0:1], s[0:1], 12
	s_waitcnt lgkmcnt(0)
	s_add_u32 s2, s2, s0
	v_ashrrev_i32_e32 v5, 31, v4
	s_addc_u32 s3, s3, s1
	v_lshlrev_b64 v[2:3], 2, v[4:5]
	v_lshl_add_u64 v[6:7], s[2:3], 0, v[2:3]
	s_lshl_b64 s[2:3], s[38:39], 10
	global_load_dword v0, v[6:7], off
	v_lshl_add_u64 v[6:7], s[2:3], 0, v[4:5]
	v_lshlrev_b64 v[8:9], 2, v[6:7]
	v_lshl_add_u64 v[10:11], s[52:53], 0, v[8:9]
	v_lshl_add_u64 v[8:9], s[54:55], 0, v[8:9]
	v_lshl_add_u64 v[6:7], v[6:7], 1, s[72:73]
	s_load_dwordx2 s[2:3], s[60:61], 0x140
	v_add_co_u32_e32 v10, vcc, 0x1000, v10
	s_nop 1
	v_addc_co_u32_e32 v11, vcc, 0, v11, vcc
	v_add_co_u32_e32 v8, vcc, 0x1000, v8
	s_nop 1
	v_addc_co_u32_e32 v9, vcc, 0, v9, vcc
	v_add_co_u32_e32 v6, vcc, 0x1000, v6
	s_nop 1
	v_addc_co_u32_e32 v7, vcc, 0, v7, vcc
	global_load_dword v12, v[10:11], off offset:-4096
	global_load_dword v13, v[10:11], off
	global_load_dword v5, v[8:9], off offset:-4096
	global_load_dword v4, v[8:9], off
	v_add_co_u32_e32 v10, vcc, 0x2000, v10
	s_nop 1
	v_addc_co_u32_e32 v11, vcc, 0, v11, vcc
	v_add_co_u32_e32 v8, vcc, 0x2000, v8
	s_nop 1
	v_addc_co_u32_e32 v9, vcc, 0, v9, vcc
	global_load_dword v2, v[10:11], off offset:-4096
	global_load_dword v10, v[10:11], off
	global_load_dword v3, v[8:9], off offset:-4096
	global_load_dword v8, v[8:9], off
	s_waitcnt vmcnt(0)
	v_fmac_f32_e32 v5, v0, v12
	v_fmac_f32_e32 v4, v5, v13
	v_fmac_f32_e32 v3, v4, v2
	v_fmac_f32_e32 v8, v3, v10
	v_cvt_pk_bf16_f32 v0, v5, s0
	v_cvt_pk_bf16_f32 v12, v4, s0
	v_cvt_pk_bf16_f32 v13, v3, s0
	v_cvt_pk_bf16_f32 v10, v8, s0
	global_store_short v[6:7], v0, off offset:-4096
	global_store_short v[6:7], v12, off offset:-2048
	global_store_short v[6:7], v13, off
	global_store_short v[6:7], v10, off offset:2048
	s_lshl_b32 s38, s9, 9
	s_and_b32 s38, s38, 0x200
	v_add_u32_e32 v2, s38, v34
	v_ashrrev_i32_e32 v3, 31, v2
	v_lshlrev_b64 v[2:3], 2, v[2:3]
	s_waitcnt lgkmcnt(0)
	s_add_u32 s0, s2, s0
	s_addc_u32 s1, s3, s1
	v_lshl_add_u64 v[2:3], s[0:1], 0, v[2:3]
	v_add_co_u32_e32 v2, vcc, 0x19c0c000, v2
	s_nop 1
	v_addc_co_u32_e32 v3, vcc, 0, v3, vcc
	global_store_dword v[2:3], v8, off
	s_mov_b64 s[0:1], 0
